# attention MODE 1 epilogue: the 64 serialized LDS read-modify-write round trips on the parked O tile batched (64 reads, arithmetic, 64 writes; same instructions and operands)
# baseline (speedup 1.0000x reference)
.LBB0_393:
	s_or_b64 exec, exec, s[0:1]
	s_waitcnt lgkmcnt(0)
	v_lshl_add_u32 v78, v226, 4, s2
	ds_read_b128 v[64:67], v78 offset:128
	ds_read_b128 v[68:71], v78 offset:160
	s_lshl_b64 s[0:1], s[96:97], 11
	s_add_u32 s0, s55, s0
	s_addc_u32 s1, s56, s1
	s_waitcnt lgkmcnt(1)
	v_rcp_f32_e32 v82, v64
	v_rcp_f32_e32 v83, v65
	v_rcp_f32_e32 v84, v66
	v_rcp_f32_e32 v77, v67
	ds_read_b128 v[64:67], v78 offset:192
	ds_read_b128 v[78:81], v78 offset:224
	s_lshl_b32 s2, s34, 13
	s_add_i32 s2, s2, 0
	s_waitcnt lgkmcnt(2)
	v_rcp_f32_e32 v73, v71
	s_waitcnt lgkmcnt(1)
	v_rcp_f32_e32 v71, v65
	s_add_i32 s2, s2, 0x12800
	v_lshlrev_b32_e32 v65, 1, v224
	v_add3_u32 v65, s2, v225, v65
	v_rcp_f32_e32 v76, v68
	s_waitcnt lgkmcnt(0)
	v_rcp_f32_e32 v68, v78
	v_rcp_f32_e32 v75, v69
	v_rcp_f32_e32 v74, v70
	v_rcp_f32_e32 v72, v64
	v_rcp_f32_e32 v70, v66
	v_rcp_f32_e32 v69, v67
	v_rcp_f32_e32 v67, v79
	v_rcp_f32_e32 v66, v80
	v_rcp_f32_e32 v64, v81
	v_lshlrev_b32_e32 v204, 4, v222
	s_lshl_b64 s[4:5], s[10:11], 11
	ds_read_u16 v128, v65
	ds_read_u16 v129, v65 offset:64
	ds_read_u16 v130, v65 offset:128
	ds_read_u16 v131, v65 offset:192
	ds_read_u16 v132, v65 offset:256
	ds_read_u16 v133, v65 offset:320
	ds_read_u16 v134, v65 offset:384
	ds_read_u16 v135, v65 offset:448
	ds_read_u16 v136, v65 offset:512
	ds_read_u16 v137, v65 offset:576
	ds_read_u16 v138, v65 offset:640
	ds_read_u16 v139, v65 offset:704
	ds_read_u16 v140, v65 offset:768
	ds_read_u16 v141, v65 offset:832
	ds_read_u16 v142, v65 offset:896
	ds_read_u16 v143, v65 offset:960
	ds_read_u16 v144, v65 offset:2048
	ds_read_u16 v145, v65 offset:2112
	ds_read_u16 v146, v65 offset:2176
	ds_read_u16 v147, v65 offset:2240
	ds_read_u16 v148, v65 offset:2304
	ds_read_u16 v149, v65 offset:2368
	ds_read_u16 v150, v65 offset:2432
	ds_read_u16 v151, v65 offset:2496
	ds_read_u16 v152, v65 offset:2560
	ds_read_u16 v153, v65 offset:2624
	ds_read_u16 v154, v65 offset:2688
	ds_read_u16 v155, v65 offset:2752
	ds_read_u16 v156, v65 offset:2816
	ds_read_u16 v157, v65 offset:2880
	ds_read_u16 v158, v65 offset:2944
	ds_read_u16 v159, v65 offset:3008
	ds_read_u16 v160, v65 offset:4096
	ds_read_u16 v161, v65 offset:4160
	ds_read_u16 v162, v65 offset:4224
	ds_read_u16 v163, v65 offset:4288
	ds_read_u16 v164, v65 offset:4352
	ds_read_u16 v165, v65 offset:4416
	ds_read_u16 v166, v65 offset:4480
	ds_read_u16 v167, v65 offset:4544
	ds_read_u16 v168, v65 offset:4608
	ds_read_u16 v169, v65 offset:4672
	ds_read_u16 v170, v65 offset:4736
	ds_read_u16 v171, v65 offset:4800
	ds_read_u16 v172, v65 offset:4864
	ds_read_u16 v173, v65 offset:4928
	ds_read_u16 v174, v65 offset:4992
	ds_read_u16 v175, v65 offset:5056
	ds_read_u16 v176, v65 offset:6144
	ds_read_u16 v177, v65 offset:6208
	ds_read_u16 v178, v65 offset:6272
	ds_read_u16 v179, v65 offset:6336
	ds_read_u16 v180, v65 offset:6400
	ds_read_u16 v181, v65 offset:6464
	ds_read_u16 v182, v65 offset:6528
	ds_read_u16 v183, v65 offset:6592
	ds_read_u16 v184, v65 offset:6656
	ds_read_u16 v185, v65 offset:6720
	ds_read_u16 v186, v65 offset:6784
	ds_read_u16 v187, v65 offset:6848
	ds_read_u16 v188, v65 offset:6912
	ds_read_u16 v189, v65 offset:6976
	ds_read_u16 v190, v65 offset:7040
	ds_read_u16 v191, v65 offset:7104
	v_mul_f32_e32 v48, v48, v82
	v_mul_f32_e32 v32, v32, v82
	v_mul_f32_e32 v16, v16, v82
	v_mul_f32_e32 v0, v0, v82
	v_mul_f32_e32 v49, v49, v83
	v_mul_f32_e32 v33, v33, v83
	v_mul_f32_e32 v17, v17, v83
	v_mul_f32_e32 v1, v1, v83
	v_mul_f32_e32 v50, v50, v84
	v_mul_f32_e32 v34, v34, v84
	v_mul_f32_e32 v18, v18, v84
	v_mul_f32_e32 v2, v2, v84
	v_mul_f32_e32 v51, v51, v77
	v_mul_f32_e32 v35, v35, v77
	v_mul_f32_e32 v19, v19, v77
	v_mul_f32_e32 v3, v3, v77
	v_mul_f32_e32 v52, v52, v76
	v_mul_f32_e32 v36, v36, v76
	v_mul_f32_e32 v20, v20, v76
	v_mul_f32_e32 v4, v4, v76
	v_mul_f32_e32 v53, v53, v75
	v_mul_f32_e32 v37, v37, v75
	v_mul_f32_e32 v21, v21, v75
	v_mul_f32_e32 v5, v5, v75
	v_mul_f32_e32 v54, v54, v74
	v_mul_f32_e32 v38, v38, v74
	v_mul_f32_e32 v22, v22, v74
	v_mul_f32_e32 v6, v6, v74
	v_mul_f32_e32 v55, v55, v73
	v_mul_f32_e32 v39, v39, v73
	v_mul_f32_e32 v23, v23, v73
	v_mul_f32_e32 v7, v7, v73
	v_mul_f32_e32 v56, v56, v72
	v_mul_f32_e32 v40, v40, v72
	v_mul_f32_e32 v24, v24, v72
	v_mul_f32_e32 v8, v8, v72
	v_mul_f32_e32 v57, v57, v71
	v_mul_f32_e32 v41, v41, v71
	v_mul_f32_e32 v25, v25, v71
	v_mul_f32_e32 v9, v9, v71
	v_mul_f32_e32 v58, v58, v70
	v_mul_f32_e32 v42, v42, v70
	v_mul_f32_e32 v26, v26, v70
	v_mul_f32_e32 v10, v10, v70
	v_mul_f32_e32 v59, v59, v69
	v_mul_f32_e32 v43, v43, v69
	v_mul_f32_e32 v27, v27, v69
	v_mul_f32_e32 v11, v11, v69
	v_mul_f32_e32 v60, v60, v68
	v_mul_f32_e32 v44, v44, v68
	v_mul_f32_e32 v28, v28, v68
	v_mul_f32_e32 v12, v12, v68
	v_mul_f32_e32 v61, v61, v67
	v_mul_f32_e32 v45, v45, v67
	v_mul_f32_e32 v29, v29, v67
	v_mul_f32_e32 v13, v13, v67
	v_mul_f32_e32 v62, v62, v66
	v_mul_f32_e32 v46, v46, v66
	v_mul_f32_e32 v30, v30, v66
	v_mul_f32_e32 v14, v14, v66
	v_mul_f32_e32 v63, v63, v64
	v_mul_f32_e32 v47, v47, v64
	v_mul_f32_e32 v31, v31, v64
	v_mul_f32_e32 v15, v15, v64
	s_waitcnt lgkmcnt(0)
	v_lshlrev_b32_e32 v128, 16, v128
	v_fma_f32 v48, -v217, v48, v128
	v_cvt_pk_bf16_f32 v48, v48, s0
	ds_write_b16 v65, v48
	v_lshlrev_b32_e32 v129, 16, v129
	v_fma_f32 v32, -v217, v32, v129
	v_cvt_pk_bf16_f32 v32, v32, s0
	ds_write_b16 v65, v32 offset:64
	v_lshlrev_b32_e32 v130, 16, v130
	v_fma_f32 v16, -v217, v16, v130
	v_cvt_pk_bf16_f32 v16, v16, s0
	ds_write_b16 v65, v16 offset:128
	v_lshlrev_b32_e32 v131, 16, v131
	v_fma_f32 v0, -v217, v0, v131
	v_cvt_pk_bf16_f32 v0, v0, s0
	ds_write_b16 v65, v0 offset:192
	v_lshlrev_b32_e32 v132, 16, v132
	v_fma_f32 v49, -v217, v49, v132
	v_cvt_pk_bf16_f32 v49, v49, s0
	ds_write_b16 v65, v49 offset:256
	v_lshlrev_b32_e32 v133, 16, v133
	v_fma_f32 v33, -v217, v33, v133
	v_cvt_pk_bf16_f32 v33, v33, s0
	ds_write_b16 v65, v33 offset:320
	v_lshlrev_b32_e32 v134, 16, v134
	v_fma_f32 v17, -v217, v17, v134
	v_cvt_pk_bf16_f32 v17, v17, s0
	ds_write_b16 v65, v17 offset:384
	v_lshlrev_b32_e32 v135, 16, v135
	v_fma_f32 v1, -v217, v1, v135
	v_cvt_pk_bf16_f32 v1, v1, s0
	ds_write_b16 v65, v1 offset:448
	v_lshlrev_b32_e32 v136, 16, v136
	v_fma_f32 v50, -v217, v50, v136
	v_cvt_pk_bf16_f32 v50, v50, s0
	ds_write_b16 v65, v50 offset:512
	v_lshlrev_b32_e32 v137, 16, v137
	v_fma_f32 v34, -v217, v34, v137
	v_cvt_pk_bf16_f32 v34, v34, s0
	ds_write_b16 v65, v34 offset:576
	v_lshlrev_b32_e32 v138, 16, v138
	v_fma_f32 v18, -v217, v18, v138
	v_cvt_pk_bf16_f32 v18, v18, s0
	ds_write_b16 v65, v18 offset:640
	v_lshlrev_b32_e32 v139, 16, v139
	v_fma_f32 v2, -v217, v2, v139
	v_cvt_pk_bf16_f32 v2, v2, s0
	ds_write_b16 v65, v2 offset:704
	v_lshlrev_b32_e32 v140, 16, v140
	v_fma_f32 v51, -v217, v51, v140
	v_cvt_pk_bf16_f32 v51, v51, s0
	ds_write_b16 v65, v51 offset:768
	v_lshlrev_b32_e32 v141, 16, v141
	v_fma_f32 v35, -v217, v35, v141
	v_cvt_pk_bf16_f32 v35, v35, s0
	ds_write_b16 v65, v35 offset:832
	v_lshlrev_b32_e32 v142, 16, v142
	v_fma_f32 v19, -v217, v19, v142
	v_cvt_pk_bf16_f32 v19, v19, s0
	ds_write_b16 v65, v19 offset:896
	v_lshlrev_b32_e32 v143, 16, v143
	v_fma_f32 v3, -v217, v3, v143
	v_cvt_pk_bf16_f32 v3, v3, s0
	ds_write_b16 v65, v3 offset:960
	v_lshlrev_b32_e32 v144, 16, v144
	v_fma_f32 v52, -v217, v52, v144
	v_cvt_pk_bf16_f32 v52, v52, s0
	ds_write_b16 v65, v52 offset:2048
	v_lshlrev_b32_e32 v145, 16, v145
	v_fma_f32 v36, -v217, v36, v145
	v_cvt_pk_bf16_f32 v36, v36, s0
	ds_write_b16 v65, v36 offset:2112
	v_lshlrev_b32_e32 v146, 16, v146
	v_fma_f32 v20, -v217, v20, v146
	v_cvt_pk_bf16_f32 v20, v20, s0
	ds_write_b16 v65, v20 offset:2176
	v_lshlrev_b32_e32 v147, 16, v147
	v_fma_f32 v4, -v217, v4, v147
	v_cvt_pk_bf16_f32 v4, v4, s0
	ds_write_b16 v65, v4 offset:2240
	v_lshlrev_b32_e32 v148, 16, v148
	v_fma_f32 v53, -v217, v53, v148
	v_cvt_pk_bf16_f32 v53, v53, s0
	ds_write_b16 v65, v53 offset:2304
	v_lshlrev_b32_e32 v149, 16, v149
	v_fma_f32 v37, -v217, v37, v149
	v_cvt_pk_bf16_f32 v37, v37, s0
	ds_write_b16 v65, v37 offset:2368
	v_lshlrev_b32_e32 v150, 16, v150
	v_fma_f32 v21, -v217, v21, v150
	v_cvt_pk_bf16_f32 v21, v21, s0
	ds_write_b16 v65, v21 offset:2432
	v_lshlrev_b32_e32 v151, 16, v151
	v_fma_f32 v5, -v217, v5, v151
	v_cvt_pk_bf16_f32 v5, v5, s0
	ds_write_b16 v65, v5 offset:2496
	v_lshlrev_b32_e32 v152, 16, v152
	v_fma_f32 v54, -v217, v54, v152
	v_cvt_pk_bf16_f32 v54, v54, s0
	ds_write_b16 v65, v54 offset:2560
	v_lshlrev_b32_e32 v153, 16, v153
	v_fma_f32 v38, -v217, v38, v153
	v_cvt_pk_bf16_f32 v38, v38, s0
	ds_write_b16 v65, v38 offset:2624
	v_lshlrev_b32_e32 v154, 16, v154
	v_fma_f32 v22, -v217, v22, v154
	v_cvt_pk_bf16_f32 v22, v22, s0
	ds_write_b16 v65, v22 offset:2688
	v_lshlrev_b32_e32 v155, 16, v155
	v_fma_f32 v6, -v217, v6, v155
	v_cvt_pk_bf16_f32 v6, v6, s0
	ds_write_b16 v65, v6 offset:2752
	v_lshlrev_b32_e32 v156, 16, v156
	v_fma_f32 v55, -v217, v55, v156
	v_cvt_pk_bf16_f32 v55, v55, s0
	ds_write_b16 v65, v55 offset:2816
	v_lshlrev_b32_e32 v157, 16, v157
	v_fma_f32 v39, -v217, v39, v157
	v_cvt_pk_bf16_f32 v39, v39, s0
	ds_write_b16 v65, v39 offset:2880
	v_lshlrev_b32_e32 v158, 16, v158
	v_fma_f32 v23, -v217, v23, v158
	v_cvt_pk_bf16_f32 v23, v23, s0
	ds_write_b16 v65, v23 offset:2944
	v_lshlrev_b32_e32 v159, 16, v159
	v_fma_f32 v7, -v217, v7, v159
	v_cvt_pk_bf16_f32 v7, v7, s0
	ds_write_b16 v65, v7 offset:3008
	v_lshlrev_b32_e32 v160, 16, v160
	v_fma_f32 v56, -v217, v56, v160
	v_cvt_pk_bf16_f32 v56, v56, s0
	ds_write_b16 v65, v56 offset:4096
	v_lshlrev_b32_e32 v161, 16, v161
	v_fma_f32 v40, -v217, v40, v161
	v_cvt_pk_bf16_f32 v40, v40, s0
	ds_write_b16 v65, v40 offset:4160
	v_lshlrev_b32_e32 v162, 16, v162
	v_fma_f32 v24, -v217, v24, v162
	v_cvt_pk_bf16_f32 v24, v24, s0
	ds_write_b16 v65, v24 offset:4224
	v_lshlrev_b32_e32 v163, 16, v163
	v_fma_f32 v8, -v217, v8, v163
	v_cvt_pk_bf16_f32 v8, v8, s0
	ds_write_b16 v65, v8 offset:4288
	v_lshlrev_b32_e32 v164, 16, v164
	v_fma_f32 v57, -v217, v57, v164
	v_cvt_pk_bf16_f32 v57, v57, s0
	ds_write_b16 v65, v57 offset:4352
	v_lshlrev_b32_e32 v165, 16, v165
	v_fma_f32 v41, -v217, v41, v165
	v_cvt_pk_bf16_f32 v41, v41, s0
	ds_write_b16 v65, v41 offset:4416
	v_lshlrev_b32_e32 v166, 16, v166
	v_fma_f32 v25, -v217, v25, v166
	v_cvt_pk_bf16_f32 v25, v25, s0
	ds_write_b16 v65, v25 offset:4480
	v_lshlrev_b32_e32 v167, 16, v167
	v_fma_f32 v9, -v217, v9, v167
	v_cvt_pk_bf16_f32 v9, v9, s0
	ds_write_b16 v65, v9 offset:4544
	v_lshlrev_b32_e32 v168, 16, v168
	v_fma_f32 v58, -v217, v58, v168
	v_cvt_pk_bf16_f32 v58, v58, s0
	ds_write_b16 v65, v58 offset:4608
	v_lshlrev_b32_e32 v169, 16, v169
	v_fma_f32 v42, -v217, v42, v169
	v_cvt_pk_bf16_f32 v42, v42, s0
	ds_write_b16 v65, v42 offset:4672
	v_lshlrev_b32_e32 v170, 16, v170
	v_fma_f32 v26, -v217, v26, v170
	v_cvt_pk_bf16_f32 v26, v26, s0
	ds_write_b16 v65, v26 offset:4736
	v_lshlrev_b32_e32 v171, 16, v171
	v_fma_f32 v10, -v217, v10, v171
	v_cvt_pk_bf16_f32 v10, v10, s0
	ds_write_b16 v65, v10 offset:4800
	v_lshlrev_b32_e32 v172, 16, v172
	v_fma_f32 v59, -v217, v59, v172
	v_cvt_pk_bf16_f32 v59, v59, s0
	ds_write_b16 v65, v59 offset:4864
	v_lshlrev_b32_e32 v173, 16, v173
	v_fma_f32 v43, -v217, v43, v173
	v_cvt_pk_bf16_f32 v43, v43, s0
	ds_write_b16 v65, v43 offset:4928
	v_lshlrev_b32_e32 v174, 16, v174
	v_fma_f32 v27, -v217, v27, v174
	v_cvt_pk_bf16_f32 v27, v27, s0
	ds_write_b16 v65, v27 offset:4992
	v_lshlrev_b32_e32 v175, 16, v175
	v_fma_f32 v11, -v217, v11, v175
	v_cvt_pk_bf16_f32 v11, v11, s0
	ds_write_b16 v65, v11 offset:5056
	v_lshlrev_b32_e32 v176, 16, v176
	v_fma_f32 v60, -v217, v60, v176
	v_cvt_pk_bf16_f32 v60, v60, s0
	ds_write_b16 v65, v60 offset:6144
	v_lshlrev_b32_e32 v177, 16, v177
	v_fma_f32 v44, -v217, v44, v177
	v_cvt_pk_bf16_f32 v44, v44, s0
	ds_write_b16 v65, v44 offset:6208
	v_lshlrev_b32_e32 v178, 16, v178
	v_fma_f32 v28, -v217, v28, v178
	v_cvt_pk_bf16_f32 v28, v28, s0
	ds_write_b16 v65, v28 offset:6272
	v_lshlrev_b32_e32 v179, 16, v179
	v_fma_f32 v12, -v217, v12, v179
	v_cvt_pk_bf16_f32 v12, v12, s0
	ds_write_b16 v65, v12 offset:6336
	v_lshlrev_b32_e32 v180, 16, v180
	v_fma_f32 v61, -v217, v61, v180
	v_cvt_pk_bf16_f32 v61, v61, s0
	ds_write_b16 v65, v61 offset:6400
	v_lshlrev_b32_e32 v181, 16, v181
	v_fma_f32 v45, -v217, v45, v181
	v_cvt_pk_bf16_f32 v45, v45, s0
	ds_write_b16 v65, v45 offset:6464
	v_lshlrev_b32_e32 v182, 16, v182
	v_fma_f32 v29, -v217, v29, v182
	v_cvt_pk_bf16_f32 v29, v29, s0
	ds_write_b16 v65, v29 offset:6528
	v_lshlrev_b32_e32 v183, 16, v183
	v_fma_f32 v13, -v217, v13, v183
	v_cvt_pk_bf16_f32 v13, v13, s0
	ds_write_b16 v65, v13 offset:6592
	v_lshlrev_b32_e32 v184, 16, v184
	v_fma_f32 v62, -v217, v62, v184
	v_cvt_pk_bf16_f32 v62, v62, s0
	ds_write_b16 v65, v62 offset:6656
	v_lshlrev_b32_e32 v185, 16, v185
	v_fma_f32 v46, -v217, v46, v185
	v_cvt_pk_bf16_f32 v46, v46, s0
	ds_write_b16 v65, v46 offset:6720
	v_lshlrev_b32_e32 v186, 16, v186
	v_fma_f32 v30, -v217, v30, v186
	v_cvt_pk_bf16_f32 v30, v30, s0
	ds_write_b16 v65, v30 offset:6784
	v_lshlrev_b32_e32 v187, 16, v187
	v_fma_f32 v14, -v217, v14, v187
	v_cvt_pk_bf16_f32 v14, v14, s0
	ds_write_b16 v65, v14 offset:6848
	v_lshlrev_b32_e32 v188, 16, v188
	v_fma_f32 v63, -v217, v63, v188
	v_cvt_pk_bf16_f32 v63, v63, s0
	ds_write_b16 v65, v63 offset:6912
	v_lshlrev_b32_e32 v189, 16, v189
	v_fma_f32 v47, -v217, v47, v189
	v_cvt_pk_bf16_f32 v47, v47, s0
	ds_write_b16 v65, v47 offset:6976
	v_lshlrev_b32_e32 v190, 16, v190
	v_fma_f32 v31, -v217, v31, v190
	v_cvt_pk_bf16_f32 v31, v31, s0
	ds_write_b16 v65, v31 offset:7040
	v_lshlrev_b32_e32 v191, 16, v191
	v_fma_f32 v15, -v217, v15, v191
	v_cvt_pk_bf16_f32 v15, v15, s0
	ds_write_b16 v65, v15 offset:7104
	v_lshlrev_b32_e32 v4, 5, v222
	v_add_u32_e32 v10, s2, v204
	v_lshl_add_u32 v11, v221, 8, v10
	s_waitcnt lgkmcnt(0)
	global_load_dwordx4 v[0:3], v4, s[20:21] offset:16
	s_nop 0
	global_load_dwordx4 v[4:7], v4, s[20:21]
	ds_read_b128 v[12:15], v11
	s_add_u32 s0, s0, s4
	s_addc_u32 s1, s1, s5
	v_lshl_add_u64 v[8:9], s[0:1], 0, v[204:205]
	v_lshlrev_b32_e32 v204, 11, v221
	s_waitcnt lgkmcnt(0)
	v_and_b32_e32 v17, 0xffff0000, v15
	v_and_b32_e32 v19, 0xffff0000, v14
	v_lshlrev_b32_e32 v16, 16, v15
	v_lshlrev_b32_e32 v18, 16, v14
	v_mov_b32_e32 v20, v17
	v_mov_b32_e32 v21, v19
	v_mov_b32_e32 v14, v16
	v_mov_b32_e32 v15, v18
	v_pk_mul_f32 v[20:21], v[20:21], v[20:21]
	v_and_b32_e32 v23, 0xffff0000, v12
	v_pk_fma_f32 v[14:15], v[14:15], v[14:15], v[20:21]
	v_and_b32_e32 v21, 0xffff0000, v13
	v_lshlrev_b32_e32 v20, 16, v13
	v_lshlrev_b32_e32 v22, 16, v12
	v_mov_b32_e32 v24, v23
	v_mov_b32_e32 v25, v21
	v_mov_b32_e32 v12, v22
	v_mov_b32_e32 v13, v20
	v_pk_mul_f32 v[24:25], v[24:25], v[24:25]
	s_mov_b64 s[0:1], 0
	v_pk_fma_f32 v[12:13], v[12:13], v[12:13], v[24:25]
	s_and_b64 vcc, exec, s[94:95]
	v_add_f32_e32 v11, v12, v13
	v_add_f32_e32 v11, v15, v11
	v_add_f32_e32 v11, v14, v11
	ds_bpermute_b32 v12, v212, v11
	s_waitcnt lgkmcnt(0)
	v_add_f32_e32 v11, v11, v12
	ds_bpermute_b32 v12, v213, v11
	s_waitcnt lgkmcnt(0)
	v_add_f32_e32 v11, v11, v12
	ds_bpermute_b32 v12, v214, v11
	s_waitcnt lgkmcnt(0)
	v_add_f32_e32 v11, v11, v12
	ds_bpermute_b32 v12, v216, v11
	s_waitcnt lgkmcnt(0)
	v_add_f32_e32 v11, v11, v12
	v_fmamk_f32 v11, v11, 0x3c000000, v218
	v_rsq_f32_e32 v11, v11
	s_nop 0
	v_mul_f32_e32 v24, 0x3f4ccccd, v11
	v_pk_mul_f32 v[12:13], v[24:25], v[22:23] op_sel_hi:[0,1]
	v_pk_mul_f32 v[14:15], v[24:25], v[20:21] op_sel_hi:[0,1]
	v_pk_mul_f32 v[16:17], v[24:25], v[16:17] op_sel_hi:[0,1]
	v_or_b32_e32 v11, 4, v221
	s_waitcnt vmcnt(1)
	v_pk_mul_f32 v[16:17], v[2:3], v[16:17]
	s_waitcnt vmcnt(0)
	v_pk_mul_f32 v[12:13], v[4:5], v[12:13]
	v_pk_mul_f32 v[14:15], v[6:7], v[14:15]
	v_cvt_pk_bf16_f32 v12, v12, v13
	v_cvt_pk_bf16_f32 v13, v14, v15
	v_pk_mul_f32 v[14:15], v[24:25], v[18:19] op_sel_hi:[0,1]
	v_pk_mul_f32 v[14:15], v[0:1], v[14:15]
	s_nop 0
	v_cvt_pk_bf16_f32 v14, v14, v15
	v_cvt_pk_bf16_f32 v15, v16, v17
	v_lshl_add_u64 v[16:17], v[8:9], 0, v[204:205]
	global_store_dwordx4 v[16:17], v[12:15], off
	v_lshlrev_b32_e32 v204, 11, v11
	s_nop 0
	v_lshl_add_u32 v12, v11, 8, v10
	ds_read_b128 v[12:15], v12
	v_or_b32_e32 v11, 8, v221
	s_waitcnt lgkmcnt(0)
	v_and_b32_e32 v17, 0xffff0000, v15
	v_and_b32_e32 v19, 0xffff0000, v14
	v_lshlrev_b32_e32 v16, 16, v15
	v_lshlrev_b32_e32 v18, 16, v14
	v_mov_b32_e32 v20, v17
	v_mov_b32_e32 v21, v19
	v_mov_b32_e32 v14, v16
	v_mov_b32_e32 v15, v18
	v_pk_mul_f32 v[20:21], v[20:21], v[20:21]
	v_and_b32_e32 v23, 0xffff0000, v12
	v_pk_fma_f32 v[14:15], v[14:15], v[14:15], v[20:21]
	v_and_b32_e32 v21, 0xffff0000, v13
	v_lshlrev_b32_e32 v20, 16, v13
	v_lshlrev_b32_e32 v22, 16, v12
	v_mov_b32_e32 v24, v23
	v_mov_b32_e32 v25, v21
	v_mov_b32_e32 v12, v22
	v_mov_b32_e32 v13, v20
	v_pk_mul_f32 v[24:25], v[24:25], v[24:25]
	s_nop 0
	v_pk_fma_f32 v[12:13], v[12:13], v[12:13], v[24:25]
	s_nop 0
	v_add_f32_e32 v12, v12, v13
	v_add_f32_e32 v12, v15, v12
	v_add_f32_e32 v12, v14, v12
	ds_bpermute_b32 v13, v212, v12
	s_waitcnt lgkmcnt(0)
	v_add_f32_e32 v12, v12, v13
	ds_bpermute_b32 v13, v213, v12
	s_waitcnt lgkmcnt(0)
	v_add_f32_e32 v12, v12, v13
	ds_bpermute_b32 v13, v214, v12
	s_waitcnt lgkmcnt(0)
	v_add_f32_e32 v12, v12, v13
	ds_bpermute_b32 v13, v216, v12
	s_waitcnt lgkmcnt(0)
	v_add_f32_e32 v12, v12, v13
	v_fmamk_f32 v12, v12, 0x3c000000, v218
	v_rsq_f32_e32 v12, v12
	s_nop 0
	v_mul_f32_e32 v24, 0x3f4ccccd, v12
	v_pk_mul_f32 v[12:13], v[24:25], v[22:23] op_sel_hi:[0,1]
	v_pk_mul_f32 v[14:15], v[24:25], v[20:21] op_sel_hi:[0,1]
	v_pk_mul_f32 v[12:13], v[4:5], v[12:13]
	v_pk_mul_f32 v[14:15], v[6:7], v[14:15]
	v_cvt_pk_bf16_f32 v12, v12, v13
	v_cvt_pk_bf16_f32 v13, v14, v15
	v_pk_mul_f32 v[14:15], v[24:25], v[18:19] op_sel_hi:[0,1]
	v_pk_mul_f32 v[16:17], v[24:25], v[16:17] op_sel_hi:[0,1]
	v_pk_mul_f32 v[14:15], v[0:1], v[14:15]
	v_pk_mul_f32 v[16:17], v[2:3], v[16:17]
	v_cvt_pk_bf16_f32 v14, v14, v15
	v_cvt_pk_bf16_f32 v15, v16, v17
	v_lshl_add_u64 v[16:17], v[8:9], 0, v[204:205]
	global_store_dwordx4 v[16:17], v[12:15], off
	v_lshlrev_b32_e32 v204, 11, v11
	s_nop 0
	v_lshl_add_u32 v12, v11, 8, v10
	ds_read_b128 v[12:15], v12
	v_or_b32_e32 v11, 12, v221
	s_waitcnt lgkmcnt(0)
	v_and_b32_e32 v17, 0xffff0000, v15
	v_and_b32_e32 v19, 0xffff0000, v14
	v_lshlrev_b32_e32 v16, 16, v15
	v_lshlrev_b32_e32 v18, 16, v14
	v_mov_b32_e32 v20, v17
	v_mov_b32_e32 v21, v19
	v_mov_b32_e32 v14, v16
	v_mov_b32_e32 v15, v18
	v_pk_mul_f32 v[20:21], v[20:21], v[20:21]
	v_and_b32_e32 v23, 0xffff0000, v12
	v_pk_fma_f32 v[14:15], v[14:15], v[14:15], v[20:21]
	v_and_b32_e32 v21, 0xffff0000, v13
	v_lshlrev_b32_e32 v20, 16, v13
	v_lshlrev_b32_e32 v22, 16, v12
	v_mov_b32_e32 v24, v23
	v_mov_b32_e32 v25, v21
	v_mov_b32_e32 v12, v22
	v_mov_b32_e32 v13, v20
	v_pk_mul_f32 v[24:25], v[24:25], v[24:25]
	s_nop 0
	v_pk_fma_f32 v[12:13], v[12:13], v[12:13], v[24:25]
	s_nop 0
	v_add_f32_e32 v12, v12, v13
	v_add_f32_e32 v12, v15, v12
	v_add_f32_e32 v12, v14, v12
	ds_bpermute_b32 v13, v212, v12
	s_waitcnt lgkmcnt(0)
	v_add_f32_e32 v12, v12, v13
	ds_bpermute_b32 v13, v213, v12
	s_waitcnt lgkmcnt(0)
	v_add_f32_e32 v12, v12, v13
	ds_bpermute_b32 v13, v214, v12
	s_waitcnt lgkmcnt(0)
	v_add_f32_e32 v12, v12, v13
	ds_bpermute_b32 v13, v216, v12
	s_waitcnt lgkmcnt(0)
	v_add_f32_e32 v12, v12, v13
	v_fmamk_f32 v12, v12, 0x3c000000, v218
	v_rsq_f32_e32 v12, v12
	s_nop 0
	v_mul_f32_e32 v24, 0x3f4ccccd, v12
	v_pk_mul_f32 v[12:13], v[24:25], v[22:23] op_sel_hi:[0,1]
	v_pk_mul_f32 v[14:15], v[24:25], v[20:21] op_sel_hi:[0,1]
	v_pk_mul_f32 v[12:13], v[4:5], v[12:13]
	v_pk_mul_f32 v[14:15], v[6:7], v[14:15]
	v_cvt_pk_bf16_f32 v12, v12, v13
	v_cvt_pk_bf16_f32 v13, v14, v15
	v_pk_mul_f32 v[14:15], v[24:25], v[18:19] op_sel_hi:[0,1]
	v_pk_mul_f32 v[16:17], v[24:25], v[16:17] op_sel_hi:[0,1]
	v_pk_mul_f32 v[14:15], v[0:1], v[14:15]
	v_pk_mul_f32 v[16:17], v[2:3], v[16:17]
	v_cvt_pk_bf16_f32 v14, v14, v15
	v_cvt_pk_bf16_f32 v15, v16, v17
	v_lshl_add_u64 v[16:17], v[8:9], 0, v[204:205]
	global_store_dwordx4 v[16:17], v[12:15], off
	v_lshlrev_b32_e32 v204, 11, v11
	s_nop 0
	v_lshl_add_u32 v12, v11, 8, v10
	ds_read_b128 v[12:15], v12
	v_or_b32_e32 v11, 16, v221
	s_waitcnt lgkmcnt(0)
	v_and_b32_e32 v17, 0xffff0000, v15
	v_and_b32_e32 v19, 0xffff0000, v14
	v_lshlrev_b32_e32 v16, 16, v15
	v_lshlrev_b32_e32 v18, 16, v14
	v_mov_b32_e32 v20, v17
	v_mov_b32_e32 v21, v19
	v_mov_b32_e32 v14, v16
	v_mov_b32_e32 v15, v18
	v_pk_mul_f32 v[20:21], v[20:21], v[20:21]
	v_and_b32_e32 v23, 0xffff0000, v12
	v_pk_fma_f32 v[14:15], v[14:15], v[14:15], v[20:21]
	v_and_b32_e32 v21, 0xffff0000, v13
	v_lshlrev_b32_e32 v20, 16, v13
	v_lshlrev_b32_e32 v22, 16, v12
	v_mov_b32_e32 v24, v23
	v_mov_b32_e32 v25, v21
	v_mov_b32_e32 v12, v22
	v_mov_b32_e32 v13, v20
	v_pk_mul_f32 v[24:25], v[24:25], v[24:25]
	s_nop 0
	v_pk_fma_f32 v[12:13], v[12:13], v[12:13], v[24:25]
	s_nop 0
	v_add_f32_e32 v12, v12, v13
	v_add_f32_e32 v12, v15, v12
	v_add_f32_e32 v12, v14, v12
	ds_bpermute_b32 v13, v212, v12
	s_waitcnt lgkmcnt(0)
	v_add_f32_e32 v12, v12, v13
	ds_bpermute_b32 v13, v213, v12
	s_waitcnt lgkmcnt(0)
	v_add_f32_e32 v12, v12, v13
	ds_bpermute_b32 v13, v214, v12
	s_waitcnt lgkmcnt(0)
	v_add_f32_e32 v12, v12, v13
	ds_bpermute_b32 v13, v216, v12
	s_waitcnt lgkmcnt(0)
	v_add_f32_e32 v12, v12, v13
	v_fmamk_f32 v12, v12, 0x3c000000, v218
	v_rsq_f32_e32 v12, v12
	s_nop 0
	v_mul_f32_e32 v24, 0x3f4ccccd, v12
	v_pk_mul_f32 v[12:13], v[24:25], v[22:23] op_sel_hi:[0,1]
	v_pk_mul_f32 v[14:15], v[24:25], v[20:21] op_sel_hi:[0,1]
	v_pk_mul_f32 v[12:13], v[4:5], v[12:13]
	v_pk_mul_f32 v[14:15], v[6:7], v[14:15]
	v_cvt_pk_bf16_f32 v12, v12, v13
	v_cvt_pk_bf16_f32 v13, v14, v15
	v_pk_mul_f32 v[14:15], v[24:25], v[18:19] op_sel_hi:[0,1]
	v_pk_mul_f32 v[16:17], v[24:25], v[16:17] op_sel_hi:[0,1]
	v_pk_mul_f32 v[14:15], v[0:1], v[14:15]
	v_pk_mul_f32 v[16:17], v[2:3], v[16:17]
	v_cvt_pk_bf16_f32 v14, v14, v15
	v_cvt_pk_bf16_f32 v15, v16, v17
	v_lshl_add_u64 v[16:17], v[8:9], 0, v[204:205]
	global_store_dwordx4 v[16:17], v[12:15], off
	v_lshlrev_b32_e32 v204, 11, v11
	s_nop 0
	v_lshl_add_u32 v12, v11, 8, v10
	ds_read_b128 v[12:15], v12
	v_or_b32_e32 v11, 20, v221
	s_waitcnt lgkmcnt(0)
	v_and_b32_e32 v17, 0xffff0000, v15
	v_and_b32_e32 v19, 0xffff0000, v14
	v_lshlrev_b32_e32 v16, 16, v15
	v_lshlrev_b32_e32 v18, 16, v14
	v_mov_b32_e32 v20, v17
	v_mov_b32_e32 v21, v19
	v_mov_b32_e32 v14, v16
	v_mov_b32_e32 v15, v18
	v_pk_mul_f32 v[20:21], v[20:21], v[20:21]
	v_and_b32_e32 v23, 0xffff0000, v12
	v_pk_fma_f32 v[14:15], v[14:15], v[14:15], v[20:21]
	v_and_b32_e32 v21, 0xffff0000, v13
	v_lshlrev_b32_e32 v20, 16, v13
	v_lshlrev_b32_e32 v22, 16, v12
	v_mov_b32_e32 v24, v23
	v_mov_b32_e32 v25, v21
	v_mov_b32_e32 v12, v22
	v_mov_b32_e32 v13, v20
	v_pk_mul_f32 v[24:25], v[24:25], v[24:25]
	s_nop 0
	v_pk_fma_f32 v[12:13], v[12:13], v[12:13], v[24:25]
	s_nop 0
	v_add_f32_e32 v12, v12, v13
	v_add_f32_e32 v12, v15, v12
	v_add_f32_e32 v12, v14, v12
	ds_bpermute_b32 v13, v212, v12
	s_waitcnt lgkmcnt(0)
	v_add_f32_e32 v12, v12, v13
	ds_bpermute_b32 v13, v213, v12
	s_waitcnt lgkmcnt(0)
	v_add_f32_e32 v12, v12, v13
	ds_bpermute_b32 v13, v214, v12
	s_waitcnt lgkmcnt(0)
	v_add_f32_e32 v12, v12, v13
	ds_bpermute_b32 v13, v216, v12
	s_waitcnt lgkmcnt(0)
	v_add_f32_e32 v12, v12, v13
	v_fmamk_f32 v12, v12, 0x3c000000, v218
	v_rsq_f32_e32 v12, v12
	s_nop 0
	v_mul_f32_e32 v24, 0x3f4ccccd, v12
	v_pk_mul_f32 v[12:13], v[24:25], v[22:23] op_sel_hi:[0,1]
	v_pk_mul_f32 v[14:15], v[24:25], v[20:21] op_sel_hi:[0,1]
	v_pk_mul_f32 v[12:13], v[4:5], v[12:13]
	v_pk_mul_f32 v[14:15], v[6:7], v[14:15]
	v_cvt_pk_bf16_f32 v12, v12, v13
	v_cvt_pk_bf16_f32 v13, v14, v15
	v_pk_mul_f32 v[14:15], v[24:25], v[18:19] op_sel_hi:[0,1]
	v_pk_mul_f32 v[16:17], v[24:25], v[16:17] op_sel_hi:[0,1]
	v_pk_mul_f32 v[14:15], v[0:1], v[14:15]
	v_pk_mul_f32 v[16:17], v[2:3], v[16:17]
	v_cvt_pk_bf16_f32 v14, v14, v15
	v_cvt_pk_bf16_f32 v15, v16, v17
	v_lshl_add_u64 v[16:17], v[8:9], 0, v[204:205]
	global_store_dwordx4 v[16:17], v[12:15], off
	v_lshlrev_b32_e32 v204, 11, v11
	s_nop 0
	v_lshl_add_u32 v12, v11, 8, v10
	ds_read_b128 v[12:15], v12
	v_or_b32_e32 v11, 24, v221
	s_waitcnt lgkmcnt(0)
	v_and_b32_e32 v17, 0xffff0000, v15
	v_and_b32_e32 v19, 0xffff0000, v14
	v_lshlrev_b32_e32 v16, 16, v15
	v_lshlrev_b32_e32 v18, 16, v14
	v_mov_b32_e32 v20, v17
	v_mov_b32_e32 v21, v19
	v_mov_b32_e32 v14, v16
	v_mov_b32_e32 v15, v18
	v_pk_mul_f32 v[20:21], v[20:21], v[20:21]
	v_and_b32_e32 v23, 0xffff0000, v12
	v_pk_fma_f32 v[14:15], v[14:15], v[14:15], v[20:21]
	v_and_b32_e32 v21, 0xffff0000, v13
	v_lshlrev_b32_e32 v20, 16, v13
	v_lshlrev_b32_e32 v22, 16, v12
	v_mov_b32_e32 v24, v23
	v_mov_b32_e32 v25, v21
	v_mov_b32_e32 v12, v22
	v_mov_b32_e32 v13, v20
	v_pk_mul_f32 v[24:25], v[24:25], v[24:25]
	s_nop 0
	v_pk_fma_f32 v[12:13], v[12:13], v[12:13], v[24:25]
	s_nop 0
	v_add_f32_e32 v12, v12, v13
	v_add_f32_e32 v12, v15, v12
	v_add_f32_e32 v12, v14, v12
	ds_bpermute_b32 v13, v212, v12
	s_waitcnt lgkmcnt(0)
	v_add_f32_e32 v12, v12, v13
	ds_bpermute_b32 v13, v213, v12
	s_waitcnt lgkmcnt(0)
	v_add_f32_e32 v12, v12, v13
	ds_bpermute_b32 v13, v214, v12
	s_waitcnt lgkmcnt(0)
	v_add_f32_e32 v12, v12, v13
	ds_bpermute_b32 v13, v216, v12
	s_waitcnt lgkmcnt(0)
	v_add_f32_e32 v12, v12, v13
	v_fmamk_f32 v12, v12, 0x3c000000, v218
	v_rsq_f32_e32 v12, v12
	s_nop 0
	v_mul_f32_e32 v24, 0x3f4ccccd, v12
	v_pk_mul_f32 v[12:13], v[24:25], v[22:23] op_sel_hi:[0,1]
	v_pk_mul_f32 v[14:15], v[24:25], v[20:21] op_sel_hi:[0,1]
	v_pk_mul_f32 v[12:13], v[4:5], v[12:13]
	v_pk_mul_f32 v[14:15], v[6:7], v[14:15]
	v_cvt_pk_bf16_f32 v12, v12, v13
	v_cvt_pk_bf16_f32 v13, v14, v15
	v_pk_mul_f32 v[14:15], v[24:25], v[18:19] op_sel_hi:[0,1]
	v_pk_mul_f32 v[16:17], v[24:25], v[16:17] op_sel_hi:[0,1]
	v_pk_mul_f32 v[14:15], v[0:1], v[14:15]
	v_pk_mul_f32 v[16:17], v[2:3], v[16:17]
	v_cvt_pk_bf16_f32 v14, v14, v15
	v_cvt_pk_bf16_f32 v15, v16, v17
	v_lshl_add_u64 v[16:17], v[8:9], 0, v[204:205]
	global_store_dwordx4 v[16:17], v[12:15], off
	v_lshlrev_b32_e32 v204, 11, v11
	s_nop 0
	v_lshl_add_u32 v12, v11, 8, v10
	ds_read_b128 v[12:15], v12
	s_waitcnt lgkmcnt(0)
	v_and_b32_e32 v17, 0xffff0000, v15
	v_and_b32_e32 v19, 0xffff0000, v14
	v_lshlrev_b32_e32 v16, 16, v15
	v_lshlrev_b32_e32 v18, 16, v14
	v_mov_b32_e32 v20, v17
	v_mov_b32_e32 v21, v19
	v_mov_b32_e32 v14, v16
	v_mov_b32_e32 v15, v18
	v_pk_mul_f32 v[20:21], v[20:21], v[20:21]
	v_and_b32_e32 v23, 0xffff0000, v12
	v_pk_fma_f32 v[14:15], v[14:15], v[14:15], v[20:21]
	v_and_b32_e32 v21, 0xffff0000, v13
	v_lshlrev_b32_e32 v20, 16, v13
	v_lshlrev_b32_e32 v22, 16, v12
	v_mov_b32_e32 v24, v23
	v_mov_b32_e32 v25, v21
	v_mov_b32_e32 v12, v22
	v_mov_b32_e32 v13, v20
	v_pk_mul_f32 v[24:25], v[24:25], v[24:25]
	s_nop 0
	v_pk_fma_f32 v[12:13], v[12:13], v[12:13], v[24:25]
	s_nop 0
	v_add_f32_e32 v12, v12, v13
	v_add_f32_e32 v12, v15, v12
	v_add_f32_e32 v12, v14, v12
	ds_bpermute_b32 v13, v212, v12
	s_waitcnt lgkmcnt(0)
	v_add_f32_e32 v12, v12, v13
	ds_bpermute_b32 v13, v213, v12
	s_waitcnt lgkmcnt(0)
	v_add_f32_e32 v12, v12, v13
	ds_bpermute_b32 v13, v214, v12
	s_waitcnt lgkmcnt(0)
	v_add_f32_e32 v12, v12, v13
	ds_bpermute_b32 v13, v216, v12
	s_waitcnt lgkmcnt(0)
	v_add_f32_e32 v12, v12, v13
	v_fmamk_f32 v12, v12, 0x3c000000, v218
	v_rsq_f32_e32 v12, v12
	s_nop 0
	v_mul_f32_e32 v24, 0x3f4ccccd, v12
	v_pk_mul_f32 v[12:13], v[24:25], v[22:23] op_sel_hi:[0,1]
	v_pk_mul_f32 v[14:15], v[24:25], v[20:21] op_sel_hi:[0,1]
	v_pk_mul_f32 v[12:13], v[4:5], v[12:13]
	v_pk_mul_f32 v[14:15], v[6:7], v[14:15]
	v_cvt_pk_bf16_f32 v12, v12, v13
	v_cvt_pk_bf16_f32 v13, v14, v15
	v_pk_mul_f32 v[14:15], v[24:25], v[18:19] op_sel_hi:[0,1]
	v_pk_mul_f32 v[16:17], v[24:25], v[16:17] op_sel_hi:[0,1]
	v_pk_mul_f32 v[14:15], v[0:1], v[14:15]
	v_pk_mul_f32 v[16:17], v[2:3], v[16:17]
	v_or_b32_e32 v24, 28, v221
	v_cvt_pk_bf16_f32 v14, v14, v15
	v_cvt_pk_bf16_f32 v15, v16, v17
	v_lshl_add_u64 v[16:17], v[8:9], 0, v[204:205]
	v_lshl_add_u32 v10, v24, 8, v10
	global_store_dwordx4 v[16:17], v[12:15], off
	ds_read_b128 v[10:13], v10
	v_lshlrev_b32_e32 v204, 11, v24
	s_waitcnt lgkmcnt(0)
	v_and_b32_e32 v15, 0xffff0000, v13
	v_and_b32_e32 v17, 0xffff0000, v12
	v_lshlrev_b32_e32 v14, 16, v13
	v_lshlrev_b32_e32 v16, 16, v12
	v_mov_b32_e32 v18, v15
	v_mov_b32_e32 v19, v17
	v_mov_b32_e32 v12, v14
	v_mov_b32_e32 v13, v16
	v_pk_mul_f32 v[18:19], v[18:19], v[18:19]
	v_and_b32_e32 v21, 0xffff0000, v10
	v_pk_fma_f32 v[12:13], v[12:13], v[12:13], v[18:19]
	v_and_b32_e32 v19, 0xffff0000, v11
	v_lshlrev_b32_e32 v18, 16, v11
	v_lshlrev_b32_e32 v20, 16, v10
	v_mov_b32_e32 v22, v21
	v_mov_b32_e32 v23, v19
	v_mov_b32_e32 v10, v20
	v_mov_b32_e32 v11, v18
	v_pk_mul_f32 v[22:23], v[22:23], v[22:23]
	s_nop 0
	v_pk_fma_f32 v[10:11], v[10:11], v[10:11], v[22:23]
	s_nop 0
	v_add_f32_e32 v10, v10, v11
	v_add_f32_e32 v10, v13, v10
	v_add_f32_e32 v10, v12, v10
	ds_bpermute_b32 v11, v212, v10
	s_waitcnt lgkmcnt(0)
	v_add_f32_e32 v10, v10, v11
	ds_bpermute_b32 v11, v213, v10
	s_waitcnt lgkmcnt(0)
	v_add_f32_e32 v10, v10, v11
	ds_bpermute_b32 v11, v214, v10
	s_waitcnt lgkmcnt(0)
	v_add_f32_e32 v10, v10, v11
	ds_bpermute_b32 v11, v216, v10
	s_waitcnt lgkmcnt(0)
	v_add_f32_e32 v10, v10, v11
	v_fmamk_f32 v10, v10, 0x3c000000, v218
	v_rsq_f32_e32 v10, v10
	s_nop 0
	v_mul_f32_e32 v10, 0x3f4ccccd, v10
	v_pk_mul_f32 v[12:13], v[10:11], v[20:21] op_sel_hi:[0,1]
	v_pk_mul_f32 v[4:5], v[4:5], v[12:13]
	v_pk_mul_f32 v[12:13], v[10:11], v[18:19] op_sel_hi:[0,1]
	v_pk_mul_f32 v[6:7], v[6:7], v[12:13]
	v_cvt_pk_bf16_f32 v4, v4, v5
	v_cvt_pk_bf16_f32 v5, v6, v7
	v_pk_mul_f32 v[6:7], v[10:11], v[16:17] op_sel_hi:[0,1]
	v_pk_mul_f32 v[0:1], v[0:1], v[6:7]
	s_nop 0
	v_cvt_pk_bf16_f32 v6, v0, v1
	v_pk_mul_f32 v[0:1], v[10:11], v[14:15] op_sel_hi:[0,1]
	v_pk_mul_f32 v[0:1], v[2:3], v[0:1]
	s_nop 0
	v_cvt_pk_bf16_f32 v7, v0, v1
	v_lshl_add_u64 v[0:1], v[8:9], 0, v[204:205]
	global_store_dwordx4 v[0:1], v[4:7], off
	s_waitcnt lgkmcnt(0)
	s_waitcnt lgkmcnt(0)
	s_barrier
	s_cbranch_vccnz .LBB0_391
